# tail tiles rebalanced over the attention workgroups: the 64 workgroups with 22 attention units take two gate-c tiles, the other 128 take one G1 tail tile and one gate-c tile
# speedup vs baseline: 1.0389x; 1.0052x over previous
.LBB0_651:
	s_sub_u32 s0, s72, 128
	s_cmp_lt_u32 s0, 128
	s_cbranch_scc0 .Lg1t_skip
	v_readlane_b32 s1, v248, 42
	v_readlane_b32 s2, v250, 7
	v_readlane_b32 s3, v250, 8
	v_readlane_b32 s4, v250, 9
	v_readlane_b32 s5, v250, 11
	v_readlane_b32 s6, v250, 12
	s_nop 3
	v_writelane_b32 v255, s1, 13
	v_writelane_b32 v255, s2, 14
	v_writelane_b32 v255, s3, 15
	v_writelane_b32 v255, s4, 16
	v_writelane_b32 v255, s5, 17
	v_writelane_b32 v255, s6, 18
	s_cmp_lt_u32 s0, 64
	s_cselect_b32 s1, 20, 17
	s_and_b32 s2, s0, 7
	s_lshl_b32 s2, s2, 3
	s_bfe_u32 s3, s0, 0x30003
	s_add_u32 s2, s2, s3
	s_lshl_b32 s3, s1, 19
	s_lshl_b32 s4, s2, 19
	s_mov_b32 s5, 0
	v_writelane_b32 v248, s1, 42
	v_writelane_b32 v250, s3, 7
	v_writelane_b32 v250, s5, 8
	v_writelane_b32 v250, s2, 9
	v_writelane_b32 v250, s4, 11
	v_writelane_b32 v250, s5, 12
	s_mov_b32 s74, 0x100000
	s_mov_b32 s101, 2
	v_readlane_b32 s4, v252, 7
	s_branch .LBB0_153

.Lg1t_skip:
	s_sub_u32 s0, s72, 64
	s_add_u32 s2, s0, 64
	s_lshl_b32 s3, s0, 1
	s_cmp_lt_u32 s0, 64
	s_cselect_b32 s1, 2, 1
	s_cselect_b32 s2, s3, s2
	v_readlane_b32 s3, v249, 58
	v_readlane_b32 s4, v249, 59
	v_readlane_b32 s5, v249, 60
	v_readlane_b32 s6, v249, 61
	v_readlane_b32 s7, v249, 63
	v_readlane_b32 s26, v250, 0
	s_nop 3
	v_writelane_b32 v255, s1, 19
	v_writelane_b32 v255, s2, 20
	v_writelane_b32 v255, s3, 21
	v_writelane_b32 v255, s4, 22
	v_writelane_b32 v255, s5, 23
	v_writelane_b32 v255, s6, 24
	v_writelane_b32 v255, s7, 25
	v_writelane_b32 v255, s26, 26
